# v6 + down GEMM (ph8/ph15) walks its two tile rounds in reverse: reads the most recently written ACT rows first, ends on the rows the PLE phase reads first
# baseline (speedup 1.0000x reference)
;     __device__ __forceinline__ bool next(int i, Unit& u) const { const int L = i * G + c; if (L >= nM * nN * ng) return false; const int per = nM * nN, r = L % per; u.g = L / per; u.pn = r / nM; u.pm = r % nM; return true; }
;     __host__ __device__ bool next(int i, Unit& u) const {
;         const long L = (long)i * G + c; if (L >= nwg) return false;
;         int wgid = (int)L; { const int q = nwg / NXCD, r = nwg % NXCD, xcd = wgid % NXCD, off = wgid / NXCD; wgid = (xcd < r ? xcd * (q + 1) : r * (q + 1) + (xcd - r) * q) + off; }
;         const int nig = WGM * nN, gid = wgid / nig, fm = gid * WGM, gsz = (nM - fm) < WGM ? (nM - fm) : WGM;
;         u.pm = fm + ((wgid % nig) % gsz); u.pn = (wgid % nig) / gsz; u.g = 0; return true;
.LBB0_752:
	s_cmp_lt_i32 s80, 9
	s_cselect_b64 s[0:1], -1, 0
	s_cmp_gt_i32 s81, 8
	s_cselect_b64 s[2:3], -1, 0
	s_and_b64 s[0:1], s[0:1], s[2:3]
	s_andn2_b64 vcc, exec, s[0:1]
	s_cbranch_vccnz .LBB0_882
	v_mov_b32_e32 v10, v0
	s_cmpk_lt_i32 s96, 0x200
	s_waitcnt lgkmcnt(0)
	s_cselect_b64 s[4:5], -1, 0
	s_cmpk_gt_i32 s96, 0x1ff
	v_readfirstlane_b32 s8, v10
	s_cbranch_scc1 .LBB0_759
	s_mov_b32 s100, s96
	s_cmp_eq_u32 s82, 0x100
	s_cbranch_scc0 .Llf8
	s_xor_b32 s100, s96, 0x100
.Llf8:
	s_ashr_i32 s0, s100, 31
	s_lshr_b32 s0, s0, 29
	s_add_i32 s0, s100, s0
	s_and_b32 s1, s0, -8
	s_sub_i32 s1, s100, s1
	s_cmp_gt_i32 s1, -1
	s_cbranch_scc0 .LBB0_756
	s_lshl_b32 s2, s1, 6
	s_cbranch_execz .LBB0_757
	s_branch .LBB0_758

;     __device__ __forceinline__ bool next(int i, Unit& u) const { const int L = i * G + c; if (L >= nM * nN * ng) return false; const int per = nM * nN, r = L % per; u.g = L / per; u.pn = r / nM; u.pm = r % nM; return true; }
;     __host__ __device__ bool next(int i, Unit& u) const {
;         const long L = (long)i * G + c; if (L >= nwg) return false;
;         int wgid = (int)L; { const int q = nwg / NXCD, r = nwg % NXCD, xcd = wgid % NXCD, off = wgid / NXCD; wgid = (xcd < r ? xcd * (q + 1) : r * (q + 1) + (xcd - r) * q) + off; }
;         const int nig = WGM * nN, gid = wgid / nig, fm = gid * WGM, gsz = (nM - fm) < WGM ? (nM - fm) : WGM;
;         u.pm = fm + ((wgid % nig) % gsz); u.pn = (wgid % nig) / gsz; u.g = 0; return true;
; template <class Epi, class Sched, bool ALIGN_EPI = false, bool SP2 = false>
; __device__ __forceinline__ void gemm_phase(PG8_LAS unsigned char* lds, const Gemm g, const Sched& S, const Epi& E) {
;     ...
;     for (;;) {
;         const bool has_next = S.next(ui + 1, nxt);
;         const char* nA = has_next ? (const char*)g.A + (size_t)nxt.g * g.gsA * 2 + (size_t)nxt.pm * tstepA : cA; const char* nB = has_next ? (const char*)g.Bt + (size_t)nxt.g * g.gsB * 2 + (size_t)nxt.pn * tstepB : cB;
.LBB0_765:
	s_add_i32 s48, s48, 1
	s_mul_i32 s4, s48, s43
	s_mul_hi_u32 s10, s48, s44
	s_add_i32 s4, s10, s4
	s_mul_i32 s10, s48, s44
	s_add_u32 s10, s10, s96
	s_addc_u32 s11, s4, s45
	v_cmp_gt_i64_e32 vcc, s[10:11], v[152:153]
	v_cmp_lt_i64_e64 s[12:13], s[10:11], v[150:151]
	s_cbranch_vccnz .LBB0_771
	s_cmp_eq_u32 s82, 0x100
	s_cselect_b32 s101, 0x100, 0
	s_xor_b32 s10, s10, s101
	s_ashr_i32 s4, s10, 31
	s_lshr_b32 s4, s4, 29
	s_add_i32 s4, s10, s4
	s_and_b32 s11, s4, -8
	s_sub_i32 s24, s10, s11
	s_cmp_gt_i32 s24, -1
	s_mov_b64 s[10:11], -1
	s_cbranch_scc0 .LBB0_768
	s_lshl_b32 s25, s24, 6
	s_mov_b64 s[10:11], 0

;     __device__ __forceinline__ bool next(int i, Unit& u) const { const int L = i * G + c; if (L >= nM * nN * ng) return false; const int per = nM * nN, r = L % per; u.g = L / per; u.pn = r / nM; u.pm = r % nM; return true; }
;     __host__ __device__ bool next(int i, Unit& u) const {
;         const long L = (long)i * G + c; if (L >= nwg) return false;
;         int wgid = (int)L; { const int q = nwg / NXCD, r = nwg % NXCD, xcd = wgid % NXCD, off = wgid / NXCD; wgid = (xcd < r ? xcd * (q + 1) : r * (q + 1) + (xcd - r) * q) + off; }
.LBB0_1614:
	s_cmp_lt_i32 s80, 16
	s_cselect_b64 s[0:1], -1, 0
	s_cmp_gt_i32 s81, 15
	s_cselect_b64 s[2:3], -1, 0
	s_and_b64 s[0:1], s[0:1], s[2:3]
	s_andn2_b64 vcc, exec, s[0:1]
	s_cbranch_vccnz .LBB0_1744
	v_mov_b32_e32 v10, v0
	s_cmpk_lt_i32 s96, 0x200
	s_waitcnt lgkmcnt(0)
	s_cselect_b64 s[4:5], -1, 0
	s_cmpk_gt_i32 s96, 0x1ff
	v_readfirstlane_b32 s8, v10
	s_cbranch_scc1 .LBB0_1621
	s_mov_b32 s100, s96
	s_cmp_eq_u32 s82, 0x100
	s_cbranch_scc0 .Llf15
	s_xor_b32 s100, s96, 0x100
